# norm-phase residual row stores nt -> plain (store-policy flip) on top of v081
# speedup vs baseline: 1.0087x; 1.0087x over previous
; __device__ __forceinline__ float lo_bf(unsigned u) { return __uint_as_float(u << 16); }
; __device__ __forceinline__ float hi_bf(unsigned u) { return __uint_as_float(u & 0xffff0000u); }
; __device__ __forceinline__ void rmsnorm_rows_bf16(int swave, const float* xsrc, const bf16_t* add, float* xdst, const float* g, bf16_t* out) {
;     ...
;   for (int row = (bidx * 8 + wave) * 2; row < TOK; row += gridDim.x * 16) {
;     const float4* xr = (const float4*)(xsrc + (size_t)row * DM);
;     float4 v[8]; float s0 = 0.f, s1 = 0.f;
; #pragma unroll
;     for (int u = 0; u < 8; ++u) { const f32x4 t = __builtin_nontemporal_load((const f32x4*)xr + lane + 64 * u); v[u] = make_float4(t[0], t[1], t[2], t[3]); }
;     if (add) {
;       const uint2* ar = (const uint2*)(add + (size_t)row * DM);
;       uint2 av[8];
; #pragma unroll
;       for (int u = 0; u < 8; ++u) av[u] = ar[lane + 64 * u];
; #pragma unroll
;       for (int u = 0; u < 8; ++u) { v[u].x += lo_bf(av[u].x); v[u].y += hi_bf(av[u].x); v[u].z += lo_bf(av[u].y); v[u].w += hi_bf(av[u].y); }
;       float4* xw = (float4*)(xdst + (size_t)row * DM);
; #pragma unroll
;       for (int u = 0; u < 8; ++u) { const f32x4 t = {v[u].x, v[u].y, v[u].z, v[u].w}; __builtin_nontemporal_store(t, (f32x4*)xw + lane + 64 * u); }
;     }
; #pragma unroll
;     for (int u = 0; u < 4; ++u) {
;       s0 += v[u].x * v[u].x + v[u].y * v[u].y + v[u].z * v[u].z + v[u].w * v[u].w;
;       s1 += v[u + 4].x * v[u + 4].x + v[u + 4].y * v[u + 4].y + v[u + 4].z * v[u + 4].z + v[u + 4].w * v[u + 4].w;
.LBB0_55:
	v_ashrrev_i32_e32 v1, 31, v0
	v_lshlrev_b64 v[32:33], 11, v[0:1]
	v_lshlrev_b64 v[34:35], 12, v[0:1]
	v_lshl_add_u64 v[20:21], v[30:31], 0, v[32:33]
	v_lshl_add_u64 v[54:55], v[24:25], 0, v[34:35]
	global_load_dwordx2 v[70:71], v[20:21], off
	global_load_dwordx2 v[72:73], v[20:21], off offset:512
	global_load_dwordx2 v[74:75], v[20:21], off offset:1024
	global_load_dwordx2 v[76:77], v[20:21], off offset:1536
	global_load_dwordx2 v[78:79], v[20:21], off offset:2048
	global_load_dwordx2 v[80:81], v[20:21], off offset:2560
	global_load_dwordx2 v[82:83], v[20:21], off offset:3072
	global_load_dwordx2 v[84:85], v[20:21], off offset:3584
	s_nop 0
	global_load_dwordx4 v[20:23], v[54:55], off nt
	global_load_dwordx4 v[42:45], v[54:55], off offset:1024 nt
	global_load_dwordx4 v[46:49], v[54:55], off offset:2048 nt
	global_load_dwordx4 v[50:53], v[54:55], off offset:3072 nt
	v_add_co_u32_e32 v66, vcc, 0x1000, v54
	v_lshl_add_u64 v[34:35], v[26:27], 0, v[34:35]
	s_nop 0
	v_addc_co_u32_e32 v67, vcc, 0, v55, vcc
	global_load_dwordx4 v[54:57], v[66:67], off nt
	global_load_dwordx4 v[58:61], v[66:67], off offset:1024 nt
	global_load_dwordx4 v[62:65], v[66:67], off offset:2048 nt
	s_nop 0
	global_load_dwordx4 v[66:69], v[66:67], off offset:3072 nt
	v_lshl_add_u64 v[32:33], v[28:29], 0, v[32:33]
	v_add_u32_e32 v0, s88, v0
	s_waitcnt vmcnt(0)
	v_lshlrev_b32_e32 v86, 16, v70
	v_and_b32_e32 v87, 0xffff0000, v70
	s_waitcnt vmcnt(14)
	v_lshlrev_b32_e32 v88, 16, v72
	v_and_b32_e32 v89, 0xffff0000, v72
	s_waitcnt vmcnt(13)
	v_lshlrev_b32_e32 v90, 16, v74
	v_and_b32_e32 v91, 0xffff0000, v74
	s_waitcnt vmcnt(12)
	v_lshlrev_b32_e32 v92, 16, v76
	v_and_b32_e32 v93, 0xffff0000, v76
	v_lshlrev_b32_e32 v76, 16, v77
	v_and_b32_e32 v77, 0xffff0000, v77
	s_waitcnt vmcnt(7)
	v_pk_add_f32 v[20:21], v[20:21], v[86:87]
	s_waitcnt vmcnt(6)
	v_pk_add_f32 v[42:43], v[42:43], v[88:89]
	s_waitcnt vmcnt(5)
	v_pk_add_f32 v[46:47], v[46:47], v[90:91]
	s_waitcnt vmcnt(4)
	v_pk_add_f32 v[50:51], v[50:51], v[92:93]
	v_lshlrev_b32_e32 v70, 16, v71
	v_and_b32_e32 v71, 0xffff0000, v71
	v_lshlrev_b32_e32 v72, 16, v73
	v_and_b32_e32 v73, 0xffff0000, v73
	v_lshlrev_b32_e32 v74, 16, v75
	v_and_b32_e32 v75, 0xffff0000, v75
	v_lshlrev_b32_e32 v94, 16, v78
	v_and_b32_e32 v95, 0xffff0000, v78
	v_lshlrev_b32_e32 v96, 16, v80
	v_and_b32_e32 v97, 0xffff0000, v80
	v_pk_add_f32 v[52:53], v[52:53], v[76:77]
	v_mov_b32_e32 v76, v21
	v_mov_b32_e32 v77, v43
	v_mov_b32_e32 v92, v47
	v_mov_b32_e32 v93, v51
	v_lshlrev_b32_e32 v80, 16, v81
	v_and_b32_e32 v81, 0xffff0000, v81
	v_pk_add_f32 v[22:23], v[22:23], v[70:71]
	v_pk_add_f32 v[44:45], v[44:45], v[72:73]
	v_pk_add_f32 v[48:49], v[48:49], v[74:75]
	v_mov_b32_e32 v74, v20
	v_mov_b32_e32 v75, v42
	v_mov_b32_e32 v90, v46
	v_mov_b32_e32 v91, v50
	v_pk_mul_f32 v[76:77], v[76:77], v[76:77]
	v_pk_mul_f32 v[92:93], v[92:93], v[92:93]
	s_waitcnt vmcnt(3)
	v_pk_add_f32 v[54:55], v[54:55], v[94:95]
	s_waitcnt vmcnt(2)
	v_pk_add_f32 v[58:59], v[58:59], v[96:97]
	v_lshlrev_b32_e32 v78, 16, v79
	v_and_b32_e32 v79, 0xffff0000, v79
	v_lshlrev_b32_e32 v98, 16, v82
	v_and_b32_e32 v99, 0xffff0000, v82
	v_lshlrev_b32_e32 v100, 16, v84
	v_and_b32_e32 v101, 0xffff0000, v84
	v_mov_b32_e32 v70, v22
	v_mov_b32_e32 v71, v44
	v_mov_b32_e32 v86, v48
	v_mov_b32_e32 v87, v52
	v_pk_fma_f32 v[74:75], v[74:75], v[74:75], v[76:77]
	v_pk_fma_f32 v[76:77], v[90:91], v[90:91], v[92:93]
	v_pk_add_f32 v[60:61], v[60:61], v[80:81]
	v_mov_b32_e32 v80, v55
	v_mov_b32_e32 v81, v59
	v_lshlrev_b32_e32 v82, 16, v83
	v_and_b32_e32 v83, 0xffff0000, v83
	v_mov_b32_e32 v72, v23
	v_mov_b32_e32 v73, v45
	v_mov_b32_e32 v88, v49
	v_mov_b32_e32 v89, v53
	v_pk_fma_f32 v[70:71], v[70:71], v[70:71], v[74:75]
	v_pk_fma_f32 v[74:75], v[86:87], v[86:87], v[76:77]
	v_pk_add_f32 v[56:57], v[56:57], v[78:79]
	v_mov_b32_e32 v78, v54
	v_mov_b32_e32 v79, v58
	v_pk_mul_f32 v[80:81], v[80:81], v[80:81]
	s_waitcnt vmcnt(1)
	v_pk_add_f32 v[62:63], v[62:63], v[98:99]
	s_waitcnt vmcnt(0)
	v_pk_add_f32 v[66:67], v[66:67], v[100:101]
	v_lshlrev_b32_e32 v84, 16, v85
	v_and_b32_e32 v85, 0xffff0000, v85
	v_pk_fma_f32 v[70:71], v[72:73], v[72:73], v[70:71]
	v_pk_fma_f32 v[72:73], v[88:89], v[88:89], v[74:75]
	v_mov_b32_e32 v74, v56
	v_mov_b32_e32 v75, v60
	v_pk_fma_f32 v[78:79], v[78:79], v[78:79], v[80:81]
	v_pk_add_f32 v[64:65], v[64:65], v[82:83]
	v_mov_b32_e32 v82, v63
	v_mov_b32_e32 v83, v67
	v_mov_b32_e32 v76, v57
	v_mov_b32_e32 v77, v61
	v_pk_fma_f32 v[74:75], v[74:75], v[74:75], v[78:79]
	v_pk_add_f32 v[68:69], v[68:69], v[84:85]
	v_mov_b32_e32 v80, v62
	v_mov_b32_e32 v81, v66
	v_pk_mul_f32 v[82:83], v[82:83], v[82:83]
	v_pk_fma_f32 v[74:75], v[76:77], v[76:77], v[74:75]
	v_mov_b32_e32 v76, v64
	v_mov_b32_e32 v77, v68
	v_pk_fma_f32 v[80:81], v[80:81], v[80:81], v[82:83]
	v_mov_b32_e32 v78, v65
	v_mov_b32_e32 v79, v69
	v_pk_fma_f32 v[76:77], v[76:77], v[76:77], v[80:81]
	global_store_dwordx4 v[34:35], v[20:23], off
	v_pk_fma_f32 v[76:77], v[78:79], v[78:79], v[76:77]
	v_mov_b32_e32 v78, v74
	v_mov_b32_e32 v79, v70
	v_mov_b32_e32 v70, v75
	v_pk_add_f32 v[70:71], v[78:79], v[70:71]
	v_mov_b32_e32 v74, v76
	v_mov_b32_e32 v75, v72
	v_pk_add_f32 v[70:71], v[70:71], v[74:75]
	v_mov_b32_e32 v72, v77
	v_pk_add_f32 v[70:71], v[70:71], v[72:73]
	ds_bpermute_b32 v73, v36, v71
	ds_bpermute_b32 v72, v36, v70
	global_store_dwordx4 v[34:35], v[42:45], off offset:1024
	global_store_dwordx4 v[34:35], v[46:49], off offset:2048
	global_store_dwordx4 v[34:35], v[50:53], off offset:3072
	v_add_co_u32_e32 v34, vcc, s62, v34
	s_waitcnt lgkmcnt(0)
; __device__ __forceinline__ unsigned pk2(float lo, float hi) { f32x2_t v = {lo, hi}; bf16x2_t b = __builtin_convertvector(v, bf16x2_t); return __builtin_bit_cast(unsigned, b); }
; __device__ __forceinline__ void rmsnorm_rows_bf16(int swave, const float* xsrc, const bf16_t* add, float* xdst, const float* g, bf16_t* out) {
;     ...
;       for (int u = 0; u < 8; ++u) { const f32x4 t = {v[u].x, v[u].y, v[u].z, v[u].w}; __builtin_nontemporal_store(t, (f32x4*)xw + lane + 64 * u); }
;     }
; #pragma unroll
;     for (int u = 0; u < 4; ++u) {
;       s0 += v[u].x * v[u].x + v[u].y * v[u].y + v[u].z * v[u].z + v[u].w * v[u].w;
;       s1 += v[u + 4].x * v[u + 4].x + v[u + 4].y * v[u + 4].y + v[u + 4].z * v[u + 4].z + v[u + 4].w * v[u + 4].w;
;     }
; #pragma unroll
;     for (int o = 32; o > 0; o >>= 1) {
;       s0 += __int_as_float(__builtin_amdgcn_ds_bpermute((lane ^ o) << 2, __float_as_int(s0)));
;       s1 += __int_as_float(__builtin_amdgcn_ds_bpermute((lane ^ o) << 2, __float_as_int(s1)));
;     }
;     const float r0 = rsqrtf(s0 * (1.f / DM) + EPS), r1 = rsqrtf(s1 * (1.f / DM) + EPS);
; #pragma unroll
;     for (int u = 0; u < 8; ++u) {
;       const float r = u < 4 ? r0 : r1; const float4 g4 = gg[u & 3];
;       uint2 o; o.x = pk2(v[u].x * r * g4.x, v[u].y * r * g4.y); o.y = pk2(v[u].z * r * g4.z, v[u].w * r * g4.w);
;       *(uint2*)(out + (size_t)row * DM + (lane + 64 * u) * 4) = o;
;     }
	v_pk_add_f32 v[70:71], v[70:71], v[72:73]
	ds_bpermute_b32 v73, v37, v71
	ds_bpermute_b32 v72, v37, v70
	v_addc_co_u32_e32 v35, vcc, 0, v35, vcc
	global_store_dwordx4 v[34:35], v[54:57], off
	global_store_dwordx4 v[34:35], v[58:61], off offset:1024
	global_store_dwordx4 v[34:35], v[62:65], off offset:2048
	global_store_dwordx4 v[34:35], v[66:69], off offset:3072
	s_waitcnt lgkmcnt(0)
	v_pk_add_f32 v[70:71], v[70:71], v[72:73]
	ds_bpermute_b32 v73, v38, v71
	ds_bpermute_b32 v72, v38, v70
	s_waitcnt lgkmcnt(0)
	v_pk_add_f32 v[70:71], v[70:71], v[72:73]
	ds_bpermute_b32 v73, v39, v71
	ds_bpermute_b32 v72, v39, v70
	s_waitcnt lgkmcnt(0)
	v_pk_add_f32 v[70:71], v[70:71], v[72:73]
	ds_bpermute_b32 v73, v40, v71
	ds_bpermute_b32 v72, v40, v70
	s_waitcnt lgkmcnt(0)
	v_pk_add_f32 v[70:71], v[70:71], v[72:73]
	ds_bpermute_b32 v73, v41, v71
	ds_bpermute_b32 v72, v41, v70
	s_waitcnt lgkmcnt(0)
	v_pk_add_f32 v[70:71], v[70:71], v[72:73]
	s_nop 0
	v_pk_fma_f32 v[70:71], v[70:71], s[12:13], v[132:133] op_sel_hi:[1,0,0]
	s_nop 0
	v_mul_f32_e32 v1, 0x4b800000, v71
	v_cmp_gt_f32_e32 vcc, s26, v71
	s_nop 1
	v_cndmask_b32_e32 v1, v71, v1, vcc
	v_rsq_f32_e32 v1, v1
	s_nop 0
	v_mul_f32_e32 v2, 0x45800000, v1
	v_cndmask_b32_e32 v2, v1, v2, vcc
	v_pk_mul_f32 v[20:21], v[20:21], v[2:3] op_sel_hi:[1,0]
	v_pk_mul_f32 v[22:23], v[22:23], v[2:3] op_sel_hi:[1,0]
	v_mul_f32_e32 v1, 0x4b800000, v70
	v_cmp_gt_f32_e32 vcc, s26, v70
	v_pk_mul_f32 v[20:21], v[4:5], v[20:21]
	v_pk_mul_f32 v[22:23], v[6:7], v[22:23]
	v_cndmask_b32_e32 v1, v70, v1, vcc
	v_cvt_pk_bf16_f32 v20, v20, v21
	v_cvt_pk_bf16_f32 v21, v22, v23
	v_pk_mul_f32 v[22:23], v[42:43], v[2:3] op_sel_hi:[1,0]
	v_pk_mul_f32 v[34:35], v[44:45], v[2:3] op_sel_hi:[1,0]
	v_rsq_f32_e32 v1, v1
	v_pk_mul_f32 v[22:23], v[8:9], v[22:23]
	v_pk_mul_f32 v[34:35], v[10:11], v[34:35]
	v_cvt_pk_bf16_f32 v22, v22, v23
	v_cvt_pk_bf16_f32 v23, v34, v35
	v_pk_mul_f32 v[34:35], v[46:47], v[2:3] op_sel_hi:[1,0]
	v_pk_mul_f32 v[42:43], v[48:49], v[2:3] op_sel_hi:[1,0]
	v_pk_mul_f32 v[34:35], v[12:13], v[34:35]
	v_pk_mul_f32 v[42:43], v[14:15], v[42:43]
	v_cvt_pk_bf16_f32 v34, v34, v35
	v_cvt_pk_bf16_f32 v35, v42, v43
	v_pk_mul_f32 v[42:43], v[50:51], v[2:3] op_sel_hi:[1,0]
	v_pk_mul_f32 v[44:45], v[52:53], v[2:3] op_sel_hi:[1,0]
	v_mul_f32_e32 v2, 0x45800000, v1
	v_pk_mul_f32 v[42:43], v[16:17], v[42:43]
	v_pk_mul_f32 v[44:45], v[18:19], v[44:45]
	v_cndmask_b32_e32 v2, v1, v2, vcc
	v_cvt_pk_bf16_f32 v42, v42, v43
	v_cvt_pk_bf16_f32 v43, v44, v45
	global_store_dwordx2 v[32:33], v[20:21], off
	global_store_dwordx2 v[32:33], v[22:23], off offset:512
	global_store_dwordx2 v[32:33], v[34:35], off offset:1024
	global_store_dwordx2 v[32:33], v[42:43], off offset:1536
	v_pk_mul_f32 v[20:21], v[54:55], v[2:3] op_sel_hi:[1,0]
	v_pk_mul_f32 v[22:23], v[56:57], v[2:3] op_sel_hi:[1,0]
	v_pk_mul_f32 v[20:21], v[4:5], v[20:21]
	v_pk_mul_f32 v[22:23], v[6:7], v[22:23]
	v_cvt_pk_bf16_f32 v20, v20, v21
	v_cvt_pk_bf16_f32 v21, v22, v23
	global_store_dwordx2 v[32:33], v[20:21], off offset:2048
	v_pk_mul_f32 v[20:21], v[58:59], v[2:3] op_sel_hi:[1,0]
	v_pk_mul_f32 v[22:23], v[60:61], v[2:3] op_sel_hi:[1,0]
	v_pk_mul_f32 v[20:21], v[8:9], v[20:21]
	v_pk_mul_f32 v[22:23], v[10:11], v[22:23]
	v_cvt_pk_bf16_f32 v20, v20, v21
	v_cvt_pk_bf16_f32 v21, v22, v23
	global_store_dwordx2 v[32:33], v[20:21], off offset:2560
	v_pk_mul_f32 v[20:21], v[62:63], v[2:3] op_sel_hi:[1,0]
	v_pk_mul_f32 v[22:23], v[64:65], v[2:3] op_sel_hi:[1,0]
	v_pk_mul_f32 v[20:21], v[12:13], v[20:21]
	v_pk_mul_f32 v[22:23], v[14:15], v[22:23]
	v_cvt_pk_bf16_f32 v20, v20, v21
	v_cvt_pk_bf16_f32 v21, v22, v23
	global_store_dwordx2 v[32:33], v[20:21], off offset:3072
	v_pk_mul_f32 v[20:21], v[66:67], v[2:3] op_sel_hi:[1,0]
	v_pk_mul_f32 v[22:23], v[68:69], v[2:3] op_sel_hi:[1,0]
	v_pk_mul_f32 v[20:21], v[16:17], v[20:21]
	v_pk_mul_f32 v[22:23], v[18:19], v[22:23]
	v_cmp_lt_i32_e32 vcc, s97, v0
	v_cvt_pk_bf16_f32 v20, v20, v21
	v_cvt_pk_bf16_f32 v21, v22, v23
	s_or_b64 s[4:5], vcc, s[4:5]
	global_store_dwordx2 v[32:33], v[20:21], off offset:3584
	s_andn2_b64 exec, exec, s[4:5]
	s_cbranch_execnz .LBB0_55

; __device__ __forceinline__ float lo_bf(unsigned u) { return __uint_as_float(u << 16); }
; __device__ __forceinline__ float hi_bf(unsigned u) { return __uint_as_float(u & 0xffff0000u); }
; __device__ __forceinline__ void rmsnorm_rows_bf16(int swave, const float* xsrc, const bf16_t* add, float* xdst, const float* g, bf16_t* out) {
;     ...
;     const float4* xr = (const float4*)(xsrc + (size_t)row * DM);
;     float4 v[8]; float s0 = 0.f, s1 = 0.f;
; #pragma unroll
;     for (int u = 0; u < 8; ++u) { const f32x4 t = __builtin_nontemporal_load((const f32x4*)xr + lane + 64 * u); v[u] = make_float4(t[0], t[1], t[2], t[3]); }
;     if (add) {
;       const uint2* ar = (const uint2*)(add + (size_t)row * DM);
;       uint2 av[8];
; #pragma unroll
;       for (int u = 0; u < 8; ++u) av[u] = ar[lane + 64 * u];
; #pragma unroll
;       for (int u = 0; u < 8; ++u) { v[u].x += lo_bf(av[u].x); v[u].y += hi_bf(av[u].x); v[u].z += lo_bf(av[u].y); v[u].w += hi_bf(av[u].y); }
;       float4* xw = (float4*)(xdst + (size_t)row * DM);
; #pragma unroll
;       for (int u = 0; u < 8; ++u) { const f32x4 t = {v[u].x, v[u].y, v[u].z, v[u].w}; __builtin_nontemporal_store(t, (f32x4*)xw + lane + 64 * u); }
;     }
; #pragma unroll
;     for (int u = 0; u < 4; ++u) {
;       s0 += v[u].x * v[u].x + v[u].y * v[u].y + v[u].z * v[u].z + v[u].w * v[u].w;
;       s1 += v[u + 4].x * v[u + 4].x + v[u + 4].y * v[u + 4].y + v[u + 4].z * v[u + 4].z + v[u + 4].w * v[u + 4].w;
;     }
; #pragma unroll
;     for (int o = 32; o > 0; o >>= 1) {
;       s0 += __int_as_float(__builtin_amdgcn_ds_bpermute((lane ^ o) << 2, __float_as_int(s0)));
;       s1 += __int_as_float(__builtin_amdgcn_ds_bpermute((lane ^ o) << 2, __float_as_int(s1)));
.LBB0_856:
	v_ashrrev_i32_e32 v1, 31, v0
	s_waitcnt vmcnt(0)
	v_lshlrev_b64 v[28:29], 11, v[0:1]
	v_lshl_add_u64 v[26:27], v[24:25], 0, v[28:29]
	global_load_dwordx2 v[54:55], v[26:27], off
	global_load_dwordx2 v[74:75], v[26:27], off offset:512
	global_load_dwordx2 v[76:77], v[26:27], off offset:1024
	global_load_dwordx2 v[78:79], v[26:27], off offset:1536
	global_load_dwordx2 v[80:81], v[26:27], off offset:2048
	global_load_dwordx2 v[82:83], v[26:27], off offset:2560
	global_load_dwordx2 v[84:85], v[26:27], off offset:3072
	global_load_dwordx2 v[86:87], v[26:27], off offset:3584
	v_lshlrev_b64 v[26:27], 12, v[0:1]
	v_lshl_add_u64 v[30:31], v[20:21], 0, v[26:27]
	global_load_dwordx4 v[38:41], v[30:31], off nt
	global_load_dwordx4 v[42:45], v[30:31], off offset:1024 nt
	global_load_dwordx4 v[46:49], v[30:31], off offset:2048 nt
	global_load_dwordx4 v[50:53], v[30:31], off offset:3072 nt
	v_add_co_u32_e32 v26, vcc, 0x1000, v30
	v_lshl_add_u64 v[28:29], v[22:23], 0, v[28:29]
	s_nop 0
	v_addc_co_u32_e32 v27, vcc, 0, v31, vcc
	global_load_dwordx4 v[58:61], v[26:27], off nt
	global_load_dwordx4 v[62:65], v[26:27], off offset:1024 nt
	global_load_dwordx4 v[66:69], v[26:27], off offset:2048 nt
	global_load_dwordx4 v[70:73], v[26:27], off offset:3072 nt
	v_add_u32_e32 v0, s88, v0
	s_waitcnt vmcnt(0)
	v_lshlrev_b32_e32 v88, 16, v54
	v_and_b32_e32 v89, 0xffff0000, v54
	v_lshlrev_b32_e32 v90, 16, v74
	v_and_b32_e32 v91, 0xffff0000, v74
	v_lshlrev_b32_e32 v92, 16, v76
	v_and_b32_e32 v93, 0xffff0000, v76
	v_lshlrev_b32_e32 v94, 16, v78
	v_and_b32_e32 v95, 0xffff0000, v78
	v_lshlrev_b32_e32 v96, 16, v80
	v_and_b32_e32 v97, 0xffff0000, v80
	v_lshlrev_b32_e32 v98, 16, v82
	v_and_b32_e32 v99, 0xffff0000, v82
	v_lshlrev_b32_e32 v74, 16, v75
	v_and_b32_e32 v75, 0xffff0000, v75
	v_lshlrev_b32_e32 v78, 16, v79
	v_and_b32_e32 v79, 0xffff0000, v79
	v_lshlrev_b32_e32 v82, 16, v83
	v_and_b32_e32 v83, 0xffff0000, v83
	v_pk_add_f32 v[38:39], v[38:39], v[88:89]
	v_pk_add_f32 v[42:43], v[42:43], v[90:91]
	v_pk_add_f32 v[46:47], v[46:47], v[92:93]
	v_pk_add_f32 v[50:51], v[50:51], v[94:95]
	v_pk_add_f32 v[58:59], v[58:59], v[96:97]
	v_pk_add_f32 v[62:63], v[62:63], v[98:99]
	v_lshlrev_b32_e32 v54, 16, v55
	v_and_b32_e32 v55, 0xffff0000, v55
	v_lshlrev_b32_e32 v76, 16, v77
	v_and_b32_e32 v77, 0xffff0000, v77
	v_lshlrev_b32_e32 v80, 16, v81
	v_and_b32_e32 v81, 0xffff0000, v81
	v_lshlrev_b32_e32 v100, 16, v84
	v_and_b32_e32 v101, 0xffff0000, v84
	v_lshlrev_b32_e32 v102, 16, v86
	v_and_b32_e32 v103, 0xffff0000, v86
	v_pk_add_f32 v[44:45], v[44:45], v[74:75]
	v_pk_add_f32 v[52:53], v[52:53], v[78:79]
	v_mov_b32_e32 v74, v39
	v_mov_b32_e32 v75, v43
	v_mov_b32_e32 v78, v47
	v_mov_b32_e32 v79, v51
	v_pk_add_f32 v[64:65], v[64:65], v[82:83]
	v_mov_b32_e32 v82, v59
	v_mov_b32_e32 v83, v63
	v_lshlrev_b32_e32 v84, 16, v85
	v_and_b32_e32 v85, 0xffff0000, v85
	v_pk_add_f32 v[40:41], v[40:41], v[54:55]
	v_pk_add_f32 v[48:49], v[48:49], v[76:77]
	v_mov_b32_e32 v54, v38
	v_mov_b32_e32 v55, v42
	v_mov_b32_e32 v76, v46
	v_mov_b32_e32 v77, v50
	v_pk_mul_f32 v[74:75], v[74:75], v[74:75]
	v_pk_mul_f32 v[78:79], v[78:79], v[78:79]
	v_pk_add_f32 v[60:61], v[60:61], v[80:81]
	v_mov_b32_e32 v80, v58
	v_mov_b32_e32 v81, v62
	v_pk_mul_f32 v[82:83], v[82:83], v[82:83]
	v_pk_add_f32 v[66:67], v[66:67], v[100:101]
	v_pk_add_f32 v[70:71], v[70:71], v[102:103]
	v_lshlrev_b32_e32 v86, 16, v87
	v_and_b32_e32 v87, 0xffff0000, v87
	v_pk_fma_f32 v[54:55], v[54:55], v[54:55], v[74:75]
	v_pk_fma_f32 v[74:75], v[76:77], v[76:77], v[78:79]
	v_mov_b32_e32 v76, v60
	v_mov_b32_e32 v77, v64
	v_pk_fma_f32 v[80:81], v[80:81], v[80:81], v[82:83]
	v_pk_add_f32 v[68:69], v[68:69], v[84:85]
	v_mov_b32_e32 v84, v67
	v_mov_b32_e32 v85, v71
	v_mov_b32_e32 v88, v40
	v_mov_b32_e32 v89, v44
	v_mov_b32_e32 v78, v61
	v_mov_b32_e32 v79, v65
	v_pk_fma_f32 v[76:77], v[76:77], v[76:77], v[80:81]
	v_pk_add_f32 v[72:73], v[72:73], v[86:87]
	v_mov_b32_e32 v82, v66
	v_mov_b32_e32 v83, v70
	v_pk_mul_f32 v[84:85], v[84:85], v[84:85]
	v_mov_b32_e32 v90, v48
	v_mov_b32_e32 v91, v52
	v_mov_b32_e32 v92, v41
	v_mov_b32_e32 v93, v45
	v_pk_fma_f32 v[54:55], v[88:89], v[88:89], v[54:55]
	v_pk_fma_f32 v[76:77], v[78:79], v[78:79], v[76:77]
	v_mov_b32_e32 v78, v68
	v_mov_b32_e32 v79, v72
	v_pk_fma_f32 v[82:83], v[82:83], v[82:83], v[84:85]
	v_mov_b32_e32 v94, v49
	v_mov_b32_e32 v95, v53
	v_pk_fma_f32 v[74:75], v[90:91], v[90:91], v[74:75]
	v_pk_fma_f32 v[54:55], v[92:93], v[92:93], v[54:55]
	v_mov_b32_e32 v80, v69
	v_mov_b32_e32 v81, v73
	v_pk_fma_f32 v[78:79], v[78:79], v[78:79], v[82:83]
	v_pk_fma_f32 v[74:75], v[94:95], v[94:95], v[74:75]
	v_pk_fma_f32 v[78:79], v[80:81], v[80:81], v[78:79]
	v_mov_b32_e32 v80, v76
	v_mov_b32_e32 v81, v54
	v_mov_b32_e32 v54, v77
	v_pk_add_f32 v[54:55], v[80:81], v[54:55]
	v_mov_b32_e32 v76, v78
	v_mov_b32_e32 v77, v74
	v_pk_add_f32 v[54:55], v[54:55], v[76:77]
	v_mov_b32_e32 v74, v79
	v_pk_add_f32 v[54:55], v[54:55], v[74:75]
	ds_bpermute_b32 v75, v32, v55
	ds_bpermute_b32 v74, v32, v54
	global_store_dwordx4 v[30:31], v[38:41], off
	global_store_dwordx4 v[30:31], v[42:45], off offset:1024
	global_store_dwordx4 v[30:31], v[46:49], off offset:2048
	global_store_dwordx4 v[30:31], v[50:53], off offset:3072
	global_store_dwordx4 v[26:27], v[58:61], off
	global_store_dwordx4 v[26:27], v[62:65], off offset:1024
	global_store_dwordx4 v[26:27], v[66:69], off offset:2048
	global_store_dwordx4 v[26:27], v[70:73], off offset:3072
	s_waitcnt lgkmcnt(0)
; __device__ __forceinline__ unsigned pk2(float lo, float hi) { f32x2_t v = {lo, hi}; bf16x2_t b = __builtin_convertvector(v, bf16x2_t); return __builtin_bit_cast(unsigned, b); }
; __device__ __forceinline__ void rmsnorm_rows_bf16(int swave, const float* xsrc, const bf16_t* add, float* xdst, const float* g, bf16_t* out) {
;     ...
;     for (int o = 32; o > 0; o >>= 1) {
;       s0 += __int_as_float(__builtin_amdgcn_ds_bpermute((lane ^ o) << 2, __float_as_int(s0)));
;       s1 += __int_as_float(__builtin_amdgcn_ds_bpermute((lane ^ o) << 2, __float_as_int(s1)));
;     }
;     const float r0 = rsqrtf(s0 * (1.f / DM) + EPS), r1 = rsqrtf(s1 * (1.f / DM) + EPS);
; #pragma unroll
;     for (int u = 0; u < 8; ++u) {
;       const float r = u < 4 ? r0 : r1; const float4 g4 = gg[u & 3];
;       uint2 o; o.x = pk2(v[u].x * r * g4.x, v[u].y * r * g4.y); o.y = pk2(v[u].z * r * g4.z, v[u].w * r * g4.w);
;       *(uint2*)(out + (size_t)row * DM + (lane + 64 * u) * 4) = o;
;     }
	v_pk_add_f32 v[54:55], v[54:55], v[74:75]
	ds_bpermute_b32 v75, v33, v55
	ds_bpermute_b32 v74, v33, v54
	s_waitcnt lgkmcnt(0)
	v_pk_add_f32 v[54:55], v[54:55], v[74:75]
	ds_bpermute_b32 v75, v34, v55
	ds_bpermute_b32 v74, v34, v54
	s_waitcnt lgkmcnt(0)
	v_pk_add_f32 v[54:55], v[54:55], v[74:75]
	ds_bpermute_b32 v75, v35, v55
	ds_bpermute_b32 v74, v35, v54
	s_waitcnt lgkmcnt(0)
	v_pk_add_f32 v[54:55], v[54:55], v[74:75]
	ds_bpermute_b32 v75, v36, v55
	ds_bpermute_b32 v74, v36, v54
	s_waitcnt lgkmcnt(0)
	v_pk_add_f32 v[54:55], v[54:55], v[74:75]
	ds_bpermute_b32 v75, v37, v55
	ds_bpermute_b32 v74, v37, v54
	s_waitcnt lgkmcnt(0)
	v_pk_add_f32 v[30:31], v[54:55], v[74:75]
	s_nop 0
	v_pk_fma_f32 v[30:31], v[30:31], s[14:15], v[132:133] op_sel_hi:[1,0,0]
	s_nop 0
	v_mul_f32_e32 v1, 0x4b800000, v31
	v_cmp_gt_f32_e32 vcc, s26, v31
	s_nop 1
	v_cndmask_b32_e32 v1, v31, v1, vcc
	v_rsq_f32_e32 v1, v1
	s_nop 0
	v_mul_f32_e32 v2, 0x45800000, v1
	v_cndmask_b32_e32 v2, v1, v2, vcc
	v_pk_mul_f32 v[26:27], v[38:39], v[2:3] op_sel_hi:[1,0]
	v_pk_mul_f32 v[38:39], v[40:41], v[2:3] op_sel_hi:[1,0]
	v_mul_f32_e32 v1, 0x4b800000, v30
	v_cmp_gt_f32_e32 vcc, s26, v30
	v_pk_mul_f32 v[26:27], v[4:5], v[26:27]
	v_pk_mul_f32 v[38:39], v[6:7], v[38:39]
	v_cndmask_b32_e32 v1, v30, v1, vcc
	v_cvt_pk_bf16_f32 v26, v26, v27
	v_cvt_pk_bf16_f32 v27, v38, v39
	v_pk_mul_f32 v[38:39], v[42:43], v[2:3] op_sel_hi:[1,0]
	v_pk_mul_f32 v[40:41], v[44:45], v[2:3] op_sel_hi:[1,0]
	v_rsq_f32_e32 v1, v1
	v_pk_mul_f32 v[38:39], v[8:9], v[38:39]
	v_pk_mul_f32 v[40:41], v[10:11], v[40:41]
	v_cvt_pk_bf16_f32 v38, v38, v39
	v_cvt_pk_bf16_f32 v39, v40, v41
	v_pk_mul_f32 v[40:41], v[46:47], v[2:3] op_sel_hi:[1,0]
	v_pk_mul_f32 v[42:43], v[48:49], v[2:3] op_sel_hi:[1,0]
	v_pk_mul_f32 v[40:41], v[12:13], v[40:41]
	v_pk_mul_f32 v[42:43], v[14:15], v[42:43]
	v_cvt_pk_bf16_f32 v40, v40, v41
	v_cvt_pk_bf16_f32 v41, v42, v43
	v_pk_mul_f32 v[42:43], v[50:51], v[2:3] op_sel_hi:[1,0]
	v_pk_mul_f32 v[30:31], v[52:53], v[2:3] op_sel_hi:[1,0]
	v_mul_f32_e32 v2, 0x45800000, v1
	v_pk_mul_f32 v[42:43], v[16:17], v[42:43]
	v_pk_mul_f32 v[30:31], v[18:19], v[30:31]
	v_cndmask_b32_e32 v2, v1, v2, vcc
	v_cvt_pk_bf16_f32 v42, v42, v43
	v_cvt_pk_bf16_f32 v43, v30, v31
	global_store_dwordx2 v[28:29], v[26:27], off
	global_store_dwordx2 v[28:29], v[38:39], off offset:512
	global_store_dwordx2 v[28:29], v[40:41], off offset:1024
	global_store_dwordx2 v[28:29], v[42:43], off offset:1536
	v_pk_mul_f32 v[26:27], v[58:59], v[2:3] op_sel_hi:[1,0]
	v_pk_mul_f32 v[30:31], v[60:61], v[2:3] op_sel_hi:[1,0]
	v_pk_mul_f32 v[26:27], v[4:5], v[26:27]
	v_pk_mul_f32 v[30:31], v[6:7], v[30:31]
	v_cvt_pk_bf16_f32 v26, v26, v27
	v_cvt_pk_bf16_f32 v27, v30, v31
	global_store_dwordx2 v[28:29], v[26:27], off offset:2048
	v_pk_mul_f32 v[26:27], v[62:63], v[2:3] op_sel_hi:[1,0]
	v_pk_mul_f32 v[30:31], v[64:65], v[2:3] op_sel_hi:[1,0]
	v_pk_mul_f32 v[26:27], v[8:9], v[26:27]
	v_pk_mul_f32 v[30:31], v[10:11], v[30:31]
	v_cvt_pk_bf16_f32 v26, v26, v27
	v_cvt_pk_bf16_f32 v27, v30, v31
	global_store_dwordx2 v[28:29], v[26:27], off offset:2560
	v_pk_mul_f32 v[26:27], v[66:67], v[2:3] op_sel_hi:[1,0]
	v_pk_mul_f32 v[30:31], v[68:69], v[2:3] op_sel_hi:[1,0]
	v_pk_mul_f32 v[26:27], v[12:13], v[26:27]
	v_pk_mul_f32 v[30:31], v[14:15], v[30:31]
	v_cvt_pk_bf16_f32 v26, v26, v27
	v_cvt_pk_bf16_f32 v27, v30, v31
	global_store_dwordx2 v[28:29], v[26:27], off offset:3072
	v_pk_mul_f32 v[26:27], v[70:71], v[2:3] op_sel_hi:[1,0]
	v_pk_mul_f32 v[30:31], v[72:73], v[2:3] op_sel_hi:[1,0]
	v_pk_mul_f32 v[26:27], v[16:17], v[26:27]
	v_pk_mul_f32 v[30:31], v[18:19], v[30:31]
	v_cmp_lt_i32_e32 vcc, s97, v0
	v_cvt_pk_bf16_f32 v26, v26, v27
	v_cvt_pk_bf16_f32 v27, v30, v31
	s_or_b64 s[2:3], vcc, s[2:3]
	global_store_dwordx2 v[28:29], v[26:27], off offset:3584
	s_andn2_b64 exec, exec, s[2:3]
	s_cbranch_execnz .LBB0_856
